# grid-barrier seams: every waiter polls the cross-XCC arrival counter (the last arrival is the release); on top of the gdn_prep stage work
# baseline (speedup 1.0000x reference)
; __device__ __forceinline__ unsigned xb_ld(unsigned* p)              { return __hip_atomic_load(p, __ATOMIC_RELAXED, __HIP_MEMORY_SCOPE_AGENT); }
; __device__ __forceinline__ unsigned xb_add(unsigned* p, unsigned v) { return __hip_atomic_fetch_add(p, v, __ATOMIC_RELAXED, __HIP_MEMORY_SCOPE_AGENT); }
; #define XB_SPIN(cond, bar) do { unsigned _sp = 0; while (cond) { __builtin_amdgcn_s_sleep(1); \
;     if ((++_sp & 255u) == 0u) { if (xb_ld(&(bar)[XB_TMO])) break; if (_sp > XB_SPIN_CAP) { atomicAdd(&(bar)[XB_TMO], 1u); break; } } } } while (0)
; __device__ __forceinline__ void xcd_barrier(const XcdBarrier& b) {
;     ...
;         const unsigned old = xb_add(&bar[XB_XSUB(b.x)], 1u);
;         const unsigned gen = old / nloc;
;         if (old + 1u == (gen + 1u) * nloc) {
;             __builtin_amdgcn_fence(__ATOMIC_RELEASE, "agent");
;             asm volatile("s_waitcnt vmcnt(0)" ::: "memory");
;             const unsigned og = xb_add(&bar[XB_TOP], 1u);
;             const unsigned tg = og / nx;
;             if (og + 1u == (tg + 1u) * nx) xb_add(&bar[XB_TOPGEN], 1u);
;             else XB_SPIN(xb_ld(&bar[XB_TOPGEN]) == tg, bar);
;             __builtin_amdgcn_fence(__ATOMIC_ACQUIRE, "agent");
;             xb_add(&bar[XB_XGEN(b.x)], 1u);
;             asm volatile("s_waitcnt vmcnt(0)" ::: "memory");
;         } else {
;             XB_SPIN(xb_ld(&bar[XB_XGEN(b.x)]) == gen, bar);
.LBB0_69:
	s_or_b64 exec, exec, s[8:9]
	v_cvt_f32_u32_e32 v6, v4
	s_waitcnt vmcnt(0)
	v_readfirstlane_b32 s2, v5
	v_sub_u32_e32 v5, 0, v4
	v_rcp_iflag_f32_e32 v6, v6
	v_add_u32_e32 v7, s2, v3
	v_mul_f32_e32 v6, 0x4f7ffffe, v6
	v_cvt_u32_f32_e32 v6, v6
	v_mul_lo_u32 v3, v5, v6
	v_mul_hi_u32 v3, v6, v3
	v_add_u32_e32 v3, v6, v3
	v_mul_hi_u32 v3, v7, v3
	v_mul_lo_u32 v5, v3, v4
	v_sub_u32_e32 v5, v7, v5
	v_add_u32_e32 v6, 1, v3
	v_cmp_ge_u32_e32 vcc, v5, v4
	s_nop 1
	v_cndmask_b32_e32 v3, v3, v6, vcc
	v_sub_u32_e32 v6, v5, v4
	v_cndmask_b32_e32 v5, v5, v6, vcc
	v_add_u32_e32 v6, 1, v3
	v_cmp_ge_u32_e32 vcc, v5, v4
	v_add_u32_e32 v5, 1, v7
	s_nop 0
	v_cndmask_b32_e32 v3, v3, v6, vcc
	v_mul_lo_u32 v6, v4, v3
	v_add_u32_e32 v4, v6, v4
	v_cmp_ne_u32_e32 vcc, v5, v4
	s_and_saveexec_b64 s[2:3], vcc
	s_xor_b64 s[6:7], exec, s[2:3]
	s_cbranch_execz .LBB0_83
	s_waitcnt lgkmcnt(0)
	buffer_inv sc1
	v_mad_u32_u24 v3, v3, v2, v2
	v_readlane_b32 s12, v239, 3
	v_readlane_b32 s13, v239, 4
	v_mov_b32_e32 v2, 0
	s_nop 1
	s_add_u32 s12, s12, 0x23400
	s_addc_u32 s13, s13, 0
	global_load_dword v2, v2, s[12:13] sc1
	s_waitcnt vmcnt(0)
	v_cmp_gt_u32_e32 vcc, v3, v2
	s_and_saveexec_b64 s[8:9], vcc
	s_cbranch_execz .LBB0_82
	v_readlane_b32 s16, v239, 1
	v_readlane_b32 s18, v239, 3
	v_readlane_b32 s19, v239, 4
	s_add_u32 s10, s18, 0x20200
	v_readlane_b32 s17, v239, 2
	s_addc_u32 s11, s19, 0
	s_mov_b32 s2, 1
	s_mov_b64 s[14:15], 0
	v_mov_b32_e32 v2, 0
	s_branch .LBB0_73

; __device__ __forceinline__ unsigned xb_ld(unsigned* p)              { return __hip_atomic_load(p, __ATOMIC_RELAXED, __HIP_MEMORY_SCOPE_AGENT); }
; #define XB_SPIN(cond, bar) do { unsigned _sp = 0; while (cond) { __builtin_amdgcn_s_sleep(1); \
;     if ((++_sp & 255u) == 0u) { if (xb_ld(&(bar)[XB_TMO])) break; if (_sp > XB_SPIN_CAP) { atomicAdd(&(bar)[XB_TMO], 1u); break; } } } } while (0)
; __device__ __forceinline__ void xcd_barrier(const XcdBarrier& b) {
;     ...
;             else XB_SPIN(xb_ld(&bar[XB_TOPGEN]) == tg, bar);
.LBB0_77:
	global_load_dword v4, v2, s[12:13] sc1
	s_add_i32 s2, s2, 1
	s_mov_b64 s[20:21], -1
	s_waitcnt vmcnt(0)
	v_cmp_le_u32_e32 vcc, v3, v4
	s_orn2_b64 s[18:19], vcc, exec
	s_branch .LBB0_72

; __device__ __forceinline__ unsigned xb_ld(unsigned* p)              { return __hip_atomic_load(p, __ATOMIC_RELAXED, __HIP_MEMORY_SCOPE_AGENT); }
; __device__ __forceinline__ unsigned xb_add(unsigned* p, unsigned v) { return __hip_atomic_fetch_add(p, v, __ATOMIC_RELAXED, __HIP_MEMORY_SCOPE_AGENT); }
; #define XB_SPIN(cond, bar) do { unsigned _sp = 0; while (cond) { __builtin_amdgcn_s_sleep(1); \
;     if ((++_sp & 255u) == 0u) { if (xb_ld(&(bar)[XB_TMO])) break; if (_sp > XB_SPIN_CAP) { atomicAdd(&(bar)[XB_TMO], 1u); break; } } } } while (0)
; __device__ __forceinline__ void xcd_barrier(const XcdBarrier& b) {
;     ...
;         const unsigned old = xb_add(&bar[XB_XSUB(b.x)], 1u);
;         const unsigned gen = old / nloc;
;         if (old + 1u == (gen + 1u) * nloc) {
;             __builtin_amdgcn_fence(__ATOMIC_RELEASE, "agent");
;             asm volatile("s_waitcnt vmcnt(0)" ::: "memory");
;             const unsigned og = xb_add(&bar[XB_TOP], 1u);
;             const unsigned tg = og / nx;
;             if (og + 1u == (tg + 1u) * nx) xb_add(&bar[XB_TOPGEN], 1u);
;             else XB_SPIN(xb_ld(&bar[XB_TOPGEN]) == tg, bar);
;             __builtin_amdgcn_fence(__ATOMIC_ACQUIRE, "agent");
;             xb_add(&bar[XB_XGEN(b.x)], 1u);
;             asm volatile("s_waitcnt vmcnt(0)" ::: "memory");
;         } else {
;             XB_SPIN(xb_ld(&bar[XB_XGEN(b.x)]) == gen, bar);
.LBB0_86:
	s_or_b64 exec, exec, s[8:9]
	v_cvt_f32_u32_e32 v5, v2
	s_waitcnt vmcnt(0)
	v_readfirstlane_b32 s2, v4
	v_readlane_b32 s8, v239, 1
	v_readlane_b32 s10, v239, 3
	v_rcp_iflag_f32_e32 v5, v5
	v_add_u32_e32 v3, s2, v3
	v_add_u32_e32 v6, 1, v3
	v_readlane_b32 s9, v239, 2
	v_mul_f32_e32 v4, 0x4f7ffffe, v5
	v_cvt_u32_f32_e32 v4, v4
	v_sub_u32_e32 v5, 0, v2
	v_readlane_b32 s11, v239, 4
	s_add_u32 s8, s10, 0x23500
	v_mul_lo_u32 v5, v5, v4
	v_mul_hi_u32 v5, v4, v5
	v_add_u32_e32 v4, v4, v5
	v_mul_hi_u32 v4, v3, v4
	v_mul_lo_u32 v5, v4, v2
	v_sub_u32_e32 v3, v3, v5
	v_add_u32_e32 v7, 1, v4
	v_cmp_ge_u32_e32 vcc, v3, v2
	v_sub_u32_e32 v5, v3, v2
	s_addc_u32 s9, s11, 0
	v_cndmask_b32_e32 v4, v4, v7, vcc
	v_cndmask_b32_e32 v3, v3, v5, vcc
	v_add_u32_e32 v5, 1, v4
	v_cmp_ge_u32_e32 vcc, v3, v2
	s_mov_b64 s[10:11], -1
	s_nop 0
	v_cndmask_b32_e32 v4, v4, v5, vcc
	v_mul_lo_u32 v3, v2, v4
	v_add_u32_e32 v2, v3, v2
	v_cmp_ne_u32_e32 vcc, v6, v2
	v_mov_b32_e32 v4, v2
	v_mov_b64_e32 v[2:3], s[8:9]
	s_and_saveexec_b64 s[6:7], vcc
	s_cbranch_execz .LBB0_98
	v_mov_b32_e32 v2, 0
	global_load_dword v3, v2, s[8:9] offset:-256 sc1
	s_mov_b64 s[14:15], 0
	s_waitcnt vmcnt(0)
	v_cmp_gt_u32_e32 vcc, v4, v3
	s_and_saveexec_b64 s[12:13], vcc
	s_cbranch_execz .LBB0_97
	v_readlane_b32 s16, v239, 1
	v_readlane_b32 s18, v239, 3
	v_readlane_b32 s19, v239, 4
	s_add_u32 s10, s18, 0x20200
	v_readlane_b32 s17, v239, 2
	s_addc_u32 s11, s19, 0
	s_mov_b32 s2, 1
	s_branch .LBB0_90

; __device__ __forceinline__ unsigned xb_ld(unsigned* p)              { return __hip_atomic_load(p, __ATOMIC_RELAXED, __HIP_MEMORY_SCOPE_AGENT); }
; #define XB_SPIN(cond, bar) do { unsigned _sp = 0; while (cond) { __builtin_amdgcn_s_sleep(1); \
;     if ((++_sp & 255u) == 0u) { if (xb_ld(&(bar)[XB_TMO])) break; if (_sp > XB_SPIN_CAP) { atomicAdd(&(bar)[XB_TMO], 1u); break; } } } } while (0)
; __device__ __forceinline__ void xcd_barrier(const XcdBarrier& b) {
;     ...
;             else XB_SPIN(xb_ld(&bar[XB_TOPGEN]) == tg, bar);
.LBB0_94:
	global_load_dword v3, v2, s[8:9] offset:-256 sc1
	s_add_i32 s2, s2, 1
	s_mov_b64 s[18:19], -1
	s_waitcnt vmcnt(0)
	v_cmp_le_u32_e32 vcc, v4, v3
	s_orn2_b64 s[22:23], vcc, exec
	s_branch .LBB0_89

; __device__ __forceinline__ unsigned xb_ld(unsigned* p)              { return __hip_atomic_load(p, __ATOMIC_RELAXED, __HIP_MEMORY_SCOPE_AGENT); }
; __device__ __forceinline__ unsigned xb_add(unsigned* p, unsigned v) { return __hip_atomic_fetch_add(p, v, __ATOMIC_RELAXED, __HIP_MEMORY_SCOPE_AGENT); }
; #define XB_SPIN(cond, bar) do { unsigned _sp = 0; while (cond) { __builtin_amdgcn_s_sleep(1); \
;     if ((++_sp & 255u) == 0u) { if (xb_ld(&(bar)[XB_TMO])) break; if (_sp > XB_SPIN_CAP) { atomicAdd(&(bar)[XB_TMO], 1u); break; } } } } while (0)
; __device__ __forceinline__ void xcd_barrier(const XcdBarrier& b) {
;     ...
;         const unsigned old = xb_add(&bar[XB_XSUB(b.x)], 1u);
;         const unsigned gen = old / nloc;
;         if (old + 1u == (gen + 1u) * nloc) {
;             __builtin_amdgcn_fence(__ATOMIC_RELEASE, "agent");
;             asm volatile("s_waitcnt vmcnt(0)" ::: "memory");
;             const unsigned og = xb_add(&bar[XB_TOP], 1u);
;             const unsigned tg = og / nx;
;             if (og + 1u == (tg + 1u) * nx) xb_add(&bar[XB_TOPGEN], 1u);
;             else XB_SPIN(xb_ld(&bar[XB_TOPGEN]) == tg, bar);
;             __builtin_amdgcn_fence(__ATOMIC_ACQUIRE, "agent");
;             xb_add(&bar[XB_XGEN(b.x)], 1u);
;             asm volatile("s_waitcnt vmcnt(0)" ::: "memory");
;         } else {
;             XB_SPIN(xb_ld(&bar[XB_XGEN(b.x)]) == gen, bar);
.LBB0_825:
	s_or_b64 exec, exec, s[10:11]
	v_cvt_f32_u32_e32 v5, v3
	s_waitcnt vmcnt(0)
	v_readfirstlane_b32 s2, v4
	v_sub_u32_e32 v4, 0, v3
	v_rcp_iflag_f32_e32 v5, v5
	v_add_u32_e32 v6, s2, v2
	v_mul_f32_e32 v5, 0x4f7ffffe, v5
	v_cvt_u32_f32_e32 v5, v5
	v_mul_lo_u32 v2, v4, v5
	v_mul_hi_u32 v2, v5, v2
	v_add_u32_e32 v2, v5, v2
	v_mul_hi_u32 v2, v6, v2
	v_mul_lo_u32 v4, v2, v3
	v_sub_u32_e32 v4, v6, v4
	v_add_u32_e32 v5, 1, v2
	v_cmp_ge_u32_e32 vcc, v4, v3
	s_nop 1
	v_cndmask_b32_e32 v2, v2, v5, vcc
	v_sub_u32_e32 v5, v4, v3
	v_cndmask_b32_e32 v4, v4, v5, vcc
	v_add_u32_e32 v5, 1, v2
	v_cmp_ge_u32_e32 vcc, v4, v3
	v_add_u32_e32 v4, 1, v6
	s_nop 0
	v_cndmask_b32_e32 v2, v2, v5, vcc
	v_mul_lo_u32 v5, v3, v2
	v_add_u32_e32 v3, v5, v3
	v_cmp_ne_u32_e32 vcc, v4, v3
	s_and_saveexec_b64 s[2:3], vcc
	s_xor_b64 s[6:7], exec, s[2:3]
	s_cbranch_execz .LBB0_839
	s_waitcnt lgkmcnt(0)
	buffer_inv sc1
	v_mad_u32_u24 v2, v2, v1, v1
	v_readlane_b32 s14, v239, 3
	v_readlane_b32 s15, v239, 4
	v_mov_b32_e32 v1, 0
	s_nop 1
	s_add_u32 s14, s14, 0x23400
	s_addc_u32 s15, s15, 0
	global_load_dword v1, v1, s[14:15] sc1
	s_waitcnt vmcnt(0)
	v_cmp_gt_u32_e32 vcc, v2, v1
	s_and_saveexec_b64 s[10:11], vcc
	s_cbranch_execz .LBB0_838
	v_readlane_b32 s16, v239, 1
	v_readlane_b32 s18, v239, 3
	v_readlane_b32 s17, v239, 2
	v_readlane_b32 s19, v239, 4
	s_add_u32 s12, s18, 0x20200
	s_addc_u32 s13, s19, 0
	s_mov_b32 s2, 1
	s_mov_b64 s[16:17], 0
	v_mov_b32_e32 v1, 0
	s_branch .LBB0_829

; __device__ __forceinline__ unsigned xb_ld(unsigned* p)              { return __hip_atomic_load(p, __ATOMIC_RELAXED, __HIP_MEMORY_SCOPE_AGENT); }
; #define XB_SPIN(cond, bar) do { unsigned _sp = 0; while (cond) { __builtin_amdgcn_s_sleep(1); \
;     if ((++_sp & 255u) == 0u) { if (xb_ld(&(bar)[XB_TMO])) break; if (_sp > XB_SPIN_CAP) { atomicAdd(&(bar)[XB_TMO], 1u); break; } } } } while (0)
; __device__ __forceinline__ void xcd_barrier(const XcdBarrier& b) {
;     ...
;             else XB_SPIN(xb_ld(&bar[XB_TOPGEN]) == tg, bar);
.LBB0_833:
	global_load_dword v3, v1, s[14:15] sc1
	s_add_i32 s2, s2, 1
	s_mov_b64 s[22:23], -1
	s_waitcnt vmcnt(0)
	v_cmp_le_u32_e32 vcc, v2, v3
	s_orn2_b64 s[20:21], vcc, exec
	s_branch .LBB0_828

; __device__ __forceinline__ unsigned xb_ld(unsigned* p)              { return __hip_atomic_load(p, __ATOMIC_RELAXED, __HIP_MEMORY_SCOPE_AGENT); }
; __device__ __forceinline__ unsigned xb_add(unsigned* p, unsigned v) { return __hip_atomic_fetch_add(p, v, __ATOMIC_RELAXED, __HIP_MEMORY_SCOPE_AGENT); }
; #define XB_SPIN(cond, bar) do { unsigned _sp = 0; while (cond) { __builtin_amdgcn_s_sleep(1); \
;     if ((++_sp & 255u) == 0u) { if (xb_ld(&(bar)[XB_TMO])) break; if (_sp > XB_SPIN_CAP) { atomicAdd(&(bar)[XB_TMO], 1u); break; } } } } while (0)
; __device__ __forceinline__ void xcd_barrier(const XcdBarrier& b) {
;     ...
;         const unsigned old = xb_add(&bar[XB_XSUB(b.x)], 1u);
;         const unsigned gen = old / nloc;
;         if (old + 1u == (gen + 1u) * nloc) {
;             __builtin_amdgcn_fence(__ATOMIC_RELEASE, "agent");
;             asm volatile("s_waitcnt vmcnt(0)" ::: "memory");
;             const unsigned og = xb_add(&bar[XB_TOP], 1u);
;             const unsigned tg = og / nx;
;             if (og + 1u == (tg + 1u) * nx) xb_add(&bar[XB_TOPGEN], 1u);
;             else XB_SPIN(xb_ld(&bar[XB_TOPGEN]) == tg, bar);
;             __builtin_amdgcn_fence(__ATOMIC_ACQUIRE, "agent");
;             xb_add(&bar[XB_XGEN(b.x)], 1u);
;             asm volatile("s_waitcnt vmcnt(0)" ::: "memory");
;         } else {
;             XB_SPIN(xb_ld(&bar[XB_XGEN(b.x)]) == gen, bar);
.LBB0_842:
	s_or_b64 exec, exec, s[10:11]
	v_cvt_f32_u32_e32 v4, v1
	s_waitcnt vmcnt(0)
	v_readfirstlane_b32 s2, v3
	v_readlane_b32 s8, v239, 1
	v_readlane_b32 s10, v239, 3
	v_rcp_iflag_f32_e32 v4, v4
	v_add_u32_e32 v2, s2, v2
	v_add_u32_e32 v5, 1, v2
	v_readlane_b32 s11, v239, 4
	v_mul_f32_e32 v3, 0x4f7ffffe, v4
	v_cvt_u32_f32_e32 v3, v3
	v_sub_u32_e32 v4, 0, v1
	s_add_u32 s10, s10, 0x23500
	s_addc_u32 s11, s11, 0
	v_mul_lo_u32 v4, v4, v3
	v_mul_hi_u32 v4, v3, v4
	v_add_u32_e32 v3, v3, v4
	v_mul_hi_u32 v3, v2, v3
	v_mul_lo_u32 v4, v3, v1
	v_sub_u32_e32 v2, v2, v4
	v_add_u32_e32 v6, 1, v3
	v_cmp_ge_u32_e32 vcc, v2, v1
	v_sub_u32_e32 v4, v2, v1
	s_mov_b64 s[12:13], -1
	v_cndmask_b32_e32 v3, v3, v6, vcc
	v_cndmask_b32_e32 v2, v2, v4, vcc
	v_add_u32_e32 v4, 1, v3
	v_cmp_ge_u32_e32 vcc, v2, v1
	v_readlane_b32 s9, v239, 2
	s_nop 0
	v_cndmask_b32_e32 v4, v3, v4, vcc
	v_mul_lo_u32 v2, v1, v4
	v_add_u32_e32 v1, v2, v1
	v_cmp_ne_u32_e32 vcc, v5, v1
	v_mov_b32_e32 v4, v1
	v_mov_b64_e32 v[2:3], s[10:11]
	s_and_saveexec_b64 s[6:7], vcc
	s_cbranch_execz .LBB0_854
	v_mov_b32_e32 v1, 0
	global_load_dword v2, v1, s[10:11] offset:-256 sc1
	s_mov_b64 s[16:17], 0
	s_waitcnt vmcnt(0)
	v_cmp_gt_u32_e32 vcc, v4, v2
	s_and_saveexec_b64 s[14:15], vcc
	s_cbranch_execz .LBB0_853
	v_readlane_b32 s16, v239, 1
	v_readlane_b32 s18, v239, 3
	v_readlane_b32 s17, v239, 2
	v_readlane_b32 s19, v239, 4
	s_add_u32 s12, s18, 0x20200
	s_addc_u32 s13, s19, 0
	s_mov_b32 s2, 1
	s_mov_b64 s[16:17], 0
	s_branch .LBB0_846

; __device__ __forceinline__ unsigned xb_ld(unsigned* p)              { return __hip_atomic_load(p, __ATOMIC_RELAXED, __HIP_MEMORY_SCOPE_AGENT); }
; #define XB_SPIN(cond, bar) do { unsigned _sp = 0; while (cond) { __builtin_amdgcn_s_sleep(1); \
;     if ((++_sp & 255u) == 0u) { if (xb_ld(&(bar)[XB_TMO])) break; if (_sp > XB_SPIN_CAP) { atomicAdd(&(bar)[XB_TMO], 1u); break; } } } } while (0)
; __device__ __forceinline__ void xcd_barrier(const XcdBarrier& b) {
;     ...
;             else XB_SPIN(xb_ld(&bar[XB_TOPGEN]) == tg, bar);
.LBB0_850:
	global_load_dword v2, v1, s[10:11] offset:-256 sc1
	s_add_i32 s2, s2, 1
	s_mov_b64 s[20:21], -1
	s_waitcnt vmcnt(0)
	v_cmp_le_u32_e32 vcc, v4, v2
	s_orn2_b64 s[24:25], vcc, exec
	s_branch .LBB0_845

; __device__ __forceinline__ unsigned xb_ld(unsigned* p)              { return __hip_atomic_load(p, __ATOMIC_RELAXED, __HIP_MEMORY_SCOPE_AGENT); }
; __device__ __forceinline__ unsigned xb_add(unsigned* p, unsigned v) { return __hip_atomic_fetch_add(p, v, __ATOMIC_RELAXED, __HIP_MEMORY_SCOPE_AGENT); }
; #define XB_SPIN(cond, bar) do { unsigned _sp = 0; while (cond) { __builtin_amdgcn_s_sleep(1); \
;     if ((++_sp & 255u) == 0u) { if (xb_ld(&(bar)[XB_TMO])) break; if (_sp > XB_SPIN_CAP) { atomicAdd(&(bar)[XB_TMO], 1u); break; } } } } while (0)
; __device__ __forceinline__ void xcd_barrier(const XcdBarrier& b) {
;     ...
;         const unsigned old = xb_add(&bar[XB_XSUB(b.x)], 1u);
;         const unsigned gen = old / nloc;
;         if (old + 1u == (gen + 1u) * nloc) {
;             __builtin_amdgcn_fence(__ATOMIC_RELEASE, "agent");
;             asm volatile("s_waitcnt vmcnt(0)" ::: "memory");
;             const unsigned og = xb_add(&bar[XB_TOP], 1u);
;             const unsigned tg = og / nx;
;             if (og + 1u == (tg + 1u) * nx) xb_add(&bar[XB_TOPGEN], 1u);
;             else XB_SPIN(xb_ld(&bar[XB_TOPGEN]) == tg, bar);
;             __builtin_amdgcn_fence(__ATOMIC_ACQUIRE, "agent");
;             xb_add(&bar[XB_XGEN(b.x)], 1u);
;             asm volatile("s_waitcnt vmcnt(0)" ::: "memory");
;         } else {
;             XB_SPIN(xb_ld(&bar[XB_XGEN(b.x)]) == gen, bar);
.LBB0_939:
	s_or_b64 exec, exec, s[12:13]
	v_cvt_f32_u32_e32 v5, v3
	s_waitcnt vmcnt(0)
	v_readfirstlane_b32 s2, v4
	v_sub_u32_e32 v4, 0, v3
	v_rcp_iflag_f32_e32 v5, v5
	v_add_u32_e32 v6, s2, v2
	v_mul_f32_e32 v5, 0x4f7ffffe, v5
	v_cvt_u32_f32_e32 v5, v5
	v_mul_lo_u32 v2, v4, v5
	v_mul_hi_u32 v2, v5, v2
	v_add_u32_e32 v2, v5, v2
	v_mul_hi_u32 v2, v6, v2
	v_mul_lo_u32 v4, v2, v3
	v_sub_u32_e32 v4, v6, v4
	v_add_u32_e32 v5, 1, v2
	v_cmp_ge_u32_e32 vcc, v4, v3
	s_nop 1
	v_cndmask_b32_e32 v2, v2, v5, vcc
	v_sub_u32_e32 v5, v4, v3
	v_cndmask_b32_e32 v4, v4, v5, vcc
	v_add_u32_e32 v5, 1, v2
	v_cmp_ge_u32_e32 vcc, v4, v3
	v_add_u32_e32 v4, 1, v6
	s_nop 0
	v_cndmask_b32_e32 v2, v2, v5, vcc
	v_mul_lo_u32 v5, v3, v2
	v_add_u32_e32 v3, v5, v3
	v_cmp_ne_u32_e32 vcc, v4, v3
	s_and_saveexec_b64 s[2:3], vcc
	s_xor_b64 s[6:7], exec, s[2:3]
	s_cbranch_execz .LBB0_953
	s_waitcnt lgkmcnt(0)
	buffer_inv sc1
	v_mad_u32_u24 v2, v2, v1, v1
	v_readlane_b32 s16, v239, 3
	v_readlane_b32 s17, v239, 4
	v_mov_b32_e32 v1, 0
	s_nop 1
	s_add_u32 s16, s16, 0x23400
	s_addc_u32 s17, s17, 0
	global_load_dword v1, v1, s[16:17] sc1
	s_waitcnt vmcnt(0)
	v_cmp_gt_u32_e32 vcc, v2, v1
	s_and_saveexec_b64 s[12:13], vcc
	s_cbranch_execz .LBB0_952
	v_readlane_b32 s20, v239, 1
	v_readlane_b32 s22, v239, 3
	v_readlane_b32 s23, v239, 4
	s_add_u32 s14, s22, 0x20200
	v_readlane_b32 s21, v239, 2
	s_addc_u32 s15, s23, 0
	s_mov_b32 s2, 1
	s_mov_b64 s[18:19], 0
	v_mov_b32_e32 v1, 0
	s_branch .LBB0_943

; __device__ __forceinline__ unsigned xb_ld(unsigned* p)              { return __hip_atomic_load(p, __ATOMIC_RELAXED, __HIP_MEMORY_SCOPE_AGENT); }
; #define XB_SPIN(cond, bar) do { unsigned _sp = 0; while (cond) { __builtin_amdgcn_s_sleep(1); \
;     if ((++_sp & 255u) == 0u) { if (xb_ld(&(bar)[XB_TMO])) break; if (_sp > XB_SPIN_CAP) { atomicAdd(&(bar)[XB_TMO], 1u); break; } } } } while (0)
; __device__ __forceinline__ void xcd_barrier(const XcdBarrier& b) {
;     ...
;             else XB_SPIN(xb_ld(&bar[XB_TOPGEN]) == tg, bar);
.LBB0_947:
	global_load_dword v3, v1, s[16:17] sc1
	s_add_i32 s2, s2, 1
	s_mov_b64 s[24:25], -1
	s_waitcnt vmcnt(0)
	v_cmp_le_u32_e32 vcc, v2, v3
	s_orn2_b64 s[22:23], vcc, exec
	s_branch .LBB0_942

; __device__ __forceinline__ unsigned xb_ld(unsigned* p)              { return __hip_atomic_load(p, __ATOMIC_RELAXED, __HIP_MEMORY_SCOPE_AGENT); }
; __device__ __forceinline__ unsigned xb_add(unsigned* p, unsigned v) { return __hip_atomic_fetch_add(p, v, __ATOMIC_RELAXED, __HIP_MEMORY_SCOPE_AGENT); }
; #define XB_SPIN(cond, bar) do { unsigned _sp = 0; while (cond) { __builtin_amdgcn_s_sleep(1); \
;     if ((++_sp & 255u) == 0u) { if (xb_ld(&(bar)[XB_TMO])) break; if (_sp > XB_SPIN_CAP) { atomicAdd(&(bar)[XB_TMO], 1u); break; } } } } while (0)
; __device__ __forceinline__ void xcd_barrier(const XcdBarrier& b) {
;     ...
;         const unsigned old = xb_add(&bar[XB_XSUB(b.x)], 1u);
;         const unsigned gen = old / nloc;
;         if (old + 1u == (gen + 1u) * nloc) {
;             __builtin_amdgcn_fence(__ATOMIC_RELEASE, "agent");
;             asm volatile("s_waitcnt vmcnt(0)" ::: "memory");
;             const unsigned og = xb_add(&bar[XB_TOP], 1u);
;             const unsigned tg = og / nx;
;             if (og + 1u == (tg + 1u) * nx) xb_add(&bar[XB_TOPGEN], 1u);
;             else XB_SPIN(xb_ld(&bar[XB_TOPGEN]) == tg, bar);
;             __builtin_amdgcn_fence(__ATOMIC_ACQUIRE, "agent");
;             xb_add(&bar[XB_XGEN(b.x)], 1u);
;             asm volatile("s_waitcnt vmcnt(0)" ::: "memory");
;         } else {
;             XB_SPIN(xb_ld(&bar[XB_XGEN(b.x)]) == gen, bar);
.LBB0_956:
	s_or_b64 exec, exec, s[12:13]
	v_cvt_f32_u32_e32 v4, v1
	s_waitcnt vmcnt(0)
	v_readfirstlane_b32 s2, v3
	v_readlane_b32 s12, v239, 1
	v_readlane_b32 s14, v239, 3
	v_rcp_iflag_f32_e32 v4, v4
	v_add_u32_e32 v2, s2, v2
	v_add_u32_e32 v5, 1, v2
	v_readlane_b32 s13, v239, 2
	v_mul_f32_e32 v3, 0x4f7ffffe, v4
	v_cvt_u32_f32_e32 v3, v3
	v_sub_u32_e32 v4, 0, v1
	v_readlane_b32 s15, v239, 4
	s_add_u32 s12, s14, 0x23500
	v_mul_lo_u32 v4, v4, v3
	v_mul_hi_u32 v4, v3, v4
	v_add_u32_e32 v3, v3, v4
	v_mul_hi_u32 v3, v2, v3
	v_mul_lo_u32 v4, v3, v1
	v_sub_u32_e32 v2, v2, v4
	v_add_u32_e32 v6, 1, v3
	v_cmp_ge_u32_e32 vcc, v2, v1
	v_sub_u32_e32 v4, v2, v1
	s_addc_u32 s13, s15, 0
	v_cndmask_b32_e32 v3, v3, v6, vcc
	v_cndmask_b32_e32 v2, v2, v4, vcc
	v_add_u32_e32 v4, 1, v3
	v_cmp_ge_u32_e32 vcc, v2, v1
	s_mov_b64 s[14:15], -1
	s_nop 0
	v_cndmask_b32_e32 v4, v3, v4, vcc
	v_mul_lo_u32 v2, v1, v4
	v_add_u32_e32 v1, v2, v1
	v_cmp_ne_u32_e32 vcc, v5, v1
	v_mov_b32_e32 v4, v1
	v_mov_b64_e32 v[2:3], s[12:13]
	s_and_saveexec_b64 s[6:7], vcc
	s_cbranch_execz .LBB0_968
	v_mov_b32_e32 v1, 0
	global_load_dword v2, v1, s[12:13] offset:-256 sc1
	s_mov_b64 s[18:19], 0
	s_waitcnt vmcnt(0)
	v_cmp_gt_u32_e32 vcc, v4, v2
	s_and_saveexec_b64 s[16:17], vcc
	s_cbranch_execz .LBB0_967
	v_readlane_b32 s20, v239, 1
	v_readlane_b32 s22, v239, 3
	v_readlane_b32 s23, v239, 4
	s_add_u32 s14, s22, 0x20200
	v_readlane_b32 s21, v239, 2
	s_addc_u32 s15, s23, 0
	s_mov_b32 s2, 1
	s_branch .LBB0_960

; __device__ __forceinline__ unsigned xb_ld(unsigned* p)              { return __hip_atomic_load(p, __ATOMIC_RELAXED, __HIP_MEMORY_SCOPE_AGENT); }
; #define XB_SPIN(cond, bar) do { unsigned _sp = 0; while (cond) { __builtin_amdgcn_s_sleep(1); \
;     if ((++_sp & 255u) == 0u) { if (xb_ld(&(bar)[XB_TMO])) break; if (_sp > XB_SPIN_CAP) { atomicAdd(&(bar)[XB_TMO], 1u); break; } } } } while (0)
; __device__ __forceinline__ void xcd_barrier(const XcdBarrier& b) {
;     ...
;             else XB_SPIN(xb_ld(&bar[XB_TOPGEN]) == tg, bar);
.LBB0_964:
	global_load_dword v2, v1, s[12:13] offset:-256 sc1
	s_add_i32 s2, s2, 1
	s_mov_b64 s[22:23], -1
	s_waitcnt vmcnt(0)
	v_cmp_le_u32_e32 vcc, v4, v2
	s_orn2_b64 s[26:27], vcc, exec
	s_branch .LBB0_959
